# adds: FFN gate/up epilogue rewritten by hand: rstd folded into the exponent scale and r^2 factor (f32), stage-wise interleaved chains without hazard nops, 32-bit saddr store addressing; 38 pct fewer i
# speedup vs baseline: 1.0106x; 1.0081x over previous
; #define LAS __attribute__((address_space(3)))
; __device__ __forceinline__ unsigned pk2(float lo, float hi) { f32x2 v = {lo, hi}; bf16x2_t b = __builtin_convertvector(v, bf16x2_t); return __builtin_bit_cast(unsigned, b); }
; __device__ __forceinline__ float silu_f(float g) { return g * __builtin_amdgcn_rcpf(1.f + __builtin_amdgcn_exp2f(g * -1.4426950408889634f)); }
;     __device__ __forceinline__ void operator()(const f32x4 (&acc)[2][2][4][2], const Unit& u, int wr, int wc, int fr, int fq, LAS unsigned char* lds, int tid, State& st) const {
;         const int row0 = u.pm * BM + wr * 64 + fr, col0 = u.pn * 128 + wc * 32 + 8 * fq;
;         const LAS float* RT = rstd_panel(st, lds, u.pm, tid);
; #pragma unroll
;         for (int ai = 0; ai < 2; ++ai) {
;             float rs[4];
; #pragma unroll
;             for (int m = 0; m < 4; ++m) rs[m] = RT[wr * 64 + fr + ai * HALF + m * 16];
; #pragma unroll
;             for (int m = 0; m < 4; ++m) {
;                 const int row = row0 + ai * HALF + m * 16; const float r = rs[m];
;                 const f32x4 g0 = acc[ai][0][m][0] * r, g1 = acc[ai][0][m][1] * r, u0 = acc[ai][1][m][0] * r, u1 = acc[ai][1][m][1] * r;
;                 u32x4 w;
;                 w.x = pk2(silu_f(g0[0]) * u0[0], silu_f(g0[1]) * u0[1]); w.y = pk2(silu_f(g0[2]) * u0[2], silu_f(g0[3]) * u0[3]);
;                 w.z = pk2(silu_f(g1[0]) * u1[0], silu_f(g1[1]) * u1[1]); w.w = pk2(silu_f(g1[2]) * u1[2], silu_f(g1[3]) * u1[3]);
;                 *(u32x4*)(H + (size_t)row * DFF + col0) = w;
;             }
.LBB0_725:
	ds_read2_b32 v[154:155], v150 offset1:16
	ds_read2_b32 v[142:143], v150 offset0:32 offset1:48
	ds_read2_b32 v[156:157], v150 offset0:128 offset1:144
	ds_read2_b32 v[144:145], v150 offset0:160 offset1:176
	s_andn2_b64 vcc, exec, s[42:43]
	v_lshl_or_b32 v216, s21, 7, v151
	v_lshl_add_u32 v217, s9, 8, v147
	v_mov_b32_e32 v204, 1.0
	v_mul_u32_u24_e32 v214, 0x1600, v217
	v_lshl_add_u32 v214, v216, 1, v214
	s_waitcnt lgkmcnt(0)
	v_mul_f32_e32 v200, 0xbfb8aa3b, v154
	v_mul_f32_e32 v202, v154, v154
	v_mov_b32_e32 v215, v214
	v_pk_mul_f32 v[206:207], v[128:129], v[200:201] op_sel_hi:[1,0]
	v_pk_mul_f32 v[208:209], v[130:131], v[200:201] op_sel_hi:[1,0]
	v_pk_mul_f32 v[210:211], v[124:125], v[200:201] op_sel_hi:[1,0]
	v_pk_mul_f32 v[212:213], v[126:127], v[200:201] op_sel_hi:[1,0]
	v_exp_f32_e32 v206, v206
	v_exp_f32_e32 v207, v207
	v_exp_f32_e32 v208, v208
	v_exp_f32_e32 v209, v209
	v_exp_f32_e32 v210, v210
	v_exp_f32_e32 v211, v211
	v_exp_f32_e32 v212, v212
	v_exp_f32_e32 v213, v213
	v_pk_mul_f32 v[120:121], v[128:129], v[120:121]
	v_pk_mul_f32 v[122:123], v[130:131], v[122:123]
	v_pk_mul_f32 v[116:117], v[124:125], v[116:117]
	v_pk_mul_f32 v[118:119], v[126:127], v[118:119]
	v_pk_add_f32 v[206:207], v[206:207], v[204:205] op_sel_hi:[1,0]
	v_pk_add_f32 v[208:209], v[208:209], v[204:205] op_sel_hi:[1,0]
	v_pk_add_f32 v[210:211], v[210:211], v[204:205] op_sel_hi:[1,0]
	v_pk_add_f32 v[212:213], v[212:213], v[204:205] op_sel_hi:[1,0]
	v_rcp_f32_e32 v206, v206
	v_rcp_f32_e32 v207, v207
	v_rcp_f32_e32 v208, v208
	v_rcp_f32_e32 v209, v209
	v_rcp_f32_e32 v210, v210
	v_rcp_f32_e32 v211, v211
	v_rcp_f32_e32 v212, v212
	v_rcp_f32_e32 v213, v213
	v_pk_mul_f32 v[120:121], v[120:121], v[202:203] op_sel_hi:[1,0]
	v_pk_mul_f32 v[122:123], v[122:123], v[202:203] op_sel_hi:[1,0]
	v_pk_mul_f32 v[116:117], v[116:117], v[202:203] op_sel_hi:[1,0]
	v_pk_mul_f32 v[118:119], v[118:119], v[202:203] op_sel_hi:[1,0]
	v_pk_mul_f32 v[120:121], v[120:121], v[206:207]
	v_pk_mul_f32 v[122:123], v[122:123], v[208:209]
	v_pk_mul_f32 v[116:117], v[116:117], v[210:211]
	v_pk_mul_f32 v[118:119], v[118:119], v[212:213]
	v_cvt_pk_bf16_f32 v120, v120, v121
	v_cvt_pk_bf16_f32 v121, v122, v123
	v_cvt_pk_bf16_f32 v122, v116, v117
	v_cvt_pk_bf16_f32 v123, v118, v119
	global_store_dwordx4 v215, v[120:123], s[94:95]
	v_mul_f32_e32 v200, 0xbfb8aa3b, v155
	v_mul_f32_e32 v202, v155, v155
	v_add_u32_e32 v215, 0x16000, v214
	v_pk_mul_f32 v[206:207], v[112:113], v[200:201] op_sel_hi:[1,0]
	v_pk_mul_f32 v[208:209], v[114:115], v[200:201] op_sel_hi:[1,0]
	v_pk_mul_f32 v[210:211], v[108:109], v[200:201] op_sel_hi:[1,0]
	v_pk_mul_f32 v[212:213], v[110:111], v[200:201] op_sel_hi:[1,0]
	v_exp_f32_e32 v206, v206
	v_exp_f32_e32 v207, v207
	v_exp_f32_e32 v208, v208
	v_exp_f32_e32 v209, v209
	v_exp_f32_e32 v210, v210
	v_exp_f32_e32 v211, v211
	v_exp_f32_e32 v212, v212
	v_exp_f32_e32 v213, v213
	v_pk_mul_f32 v[104:105], v[112:113], v[104:105]
	v_pk_mul_f32 v[106:107], v[114:115], v[106:107]
	v_pk_mul_f32 v[100:101], v[108:109], v[100:101]
	v_pk_mul_f32 v[102:103], v[110:111], v[102:103]
	v_pk_add_f32 v[206:207], v[206:207], v[204:205] op_sel_hi:[1,0]
	v_pk_add_f32 v[208:209], v[208:209], v[204:205] op_sel_hi:[1,0]
	v_pk_add_f32 v[210:211], v[210:211], v[204:205] op_sel_hi:[1,0]
	v_pk_add_f32 v[212:213], v[212:213], v[204:205] op_sel_hi:[1,0]
	v_rcp_f32_e32 v206, v206
	v_rcp_f32_e32 v207, v207
	v_rcp_f32_e32 v208, v208
	v_rcp_f32_e32 v209, v209
	v_rcp_f32_e32 v210, v210
	v_rcp_f32_e32 v211, v211
	v_rcp_f32_e32 v212, v212
	v_rcp_f32_e32 v213, v213
	v_pk_mul_f32 v[104:105], v[104:105], v[202:203] op_sel_hi:[1,0]
	v_pk_mul_f32 v[106:107], v[106:107], v[202:203] op_sel_hi:[1,0]
	v_pk_mul_f32 v[100:101], v[100:101], v[202:203] op_sel_hi:[1,0]
	v_pk_mul_f32 v[102:103], v[102:103], v[202:203] op_sel_hi:[1,0]
	v_pk_mul_f32 v[104:105], v[104:105], v[206:207]
	v_pk_mul_f32 v[106:107], v[106:107], v[208:209]
	v_pk_mul_f32 v[100:101], v[100:101], v[210:211]
	v_pk_mul_f32 v[102:103], v[102:103], v[212:213]
	v_cvt_pk_bf16_f32 v104, v104, v105
	v_cvt_pk_bf16_f32 v105, v106, v107
	v_cvt_pk_bf16_f32 v106, v100, v101
	v_cvt_pk_bf16_f32 v107, v102, v103
	global_store_dwordx4 v215, v[104:107], s[94:95]
	v_mul_f32_e32 v200, 0xbfb8aa3b, v142
	v_mul_f32_e32 v202, v142, v142
	v_add_u32_e32 v215, 0x2c000, v214
	v_pk_mul_f32 v[206:207], v[96:97], v[200:201] op_sel_hi:[1,0]
	v_pk_mul_f32 v[208:209], v[98:99], v[200:201] op_sel_hi:[1,0]
	v_pk_mul_f32 v[210:211], v[92:93], v[200:201] op_sel_hi:[1,0]
	v_pk_mul_f32 v[212:213], v[94:95], v[200:201] op_sel_hi:[1,0]
	v_exp_f32_e32 v206, v206
	v_exp_f32_e32 v207, v207
	v_exp_f32_e32 v208, v208
	v_exp_f32_e32 v209, v209
	v_exp_f32_e32 v210, v210
	v_exp_f32_e32 v211, v211
	v_exp_f32_e32 v212, v212
	v_exp_f32_e32 v213, v213
	v_pk_mul_f32 v[88:89], v[96:97], v[88:89]
	v_pk_mul_f32 v[90:91], v[98:99], v[90:91]
	v_pk_mul_f32 v[84:85], v[92:93], v[84:85]
	v_pk_mul_f32 v[86:87], v[94:95], v[86:87]
	v_pk_add_f32 v[206:207], v[206:207], v[204:205] op_sel_hi:[1,0]
	v_pk_add_f32 v[208:209], v[208:209], v[204:205] op_sel_hi:[1,0]
	v_pk_add_f32 v[210:211], v[210:211], v[204:205] op_sel_hi:[1,0]
	v_pk_add_f32 v[212:213], v[212:213], v[204:205] op_sel_hi:[1,0]
	v_rcp_f32_e32 v206, v206
	v_rcp_f32_e32 v207, v207
	v_rcp_f32_e32 v208, v208
	v_rcp_f32_e32 v209, v209
	v_rcp_f32_e32 v210, v210
	v_rcp_f32_e32 v211, v211
	v_rcp_f32_e32 v212, v212
	v_rcp_f32_e32 v213, v213
	v_pk_mul_f32 v[88:89], v[88:89], v[202:203] op_sel_hi:[1,0]
	v_pk_mul_f32 v[90:91], v[90:91], v[202:203] op_sel_hi:[1,0]
	v_pk_mul_f32 v[84:85], v[84:85], v[202:203] op_sel_hi:[1,0]
	v_pk_mul_f32 v[86:87], v[86:87], v[202:203] op_sel_hi:[1,0]
; #define LAS __attribute__((address_space(3)))
; __device__ __forceinline__ unsigned pk2(float lo, float hi) { f32x2 v = {lo, hi}; bf16x2_t b = __builtin_convertvector(v, bf16x2_t); return __builtin_bit_cast(unsigned, b); }
; __device__ __forceinline__ float silu_f(float g) { return g * __builtin_amdgcn_rcpf(1.f + __builtin_amdgcn_exp2f(g * -1.4426950408889634f)); }
;     __device__ __forceinline__ void operator()(const f32x4 (&acc)[2][2][4][2], const Unit& u, int wr, int wc, int fr, int fq, LAS unsigned char* lds, int tid, State& st) const {
;         const int row0 = u.pm * BM + wr * 64 + fr, col0 = u.pn * 128 + wc * 32 + 8 * fq;
;         const LAS float* RT = rstd_panel(st, lds, u.pm, tid);
; #pragma unroll
;         for (int ai = 0; ai < 2; ++ai) {
;             float rs[4];
; #pragma unroll
;             for (int m = 0; m < 4; ++m) rs[m] = RT[wr * 64 + fr + ai * HALF + m * 16];
; #pragma unroll
;             for (int m = 0; m < 4; ++m) {
;                 const int row = row0 + ai * HALF + m * 16; const float r = rs[m];
;                 const f32x4 g0 = acc[ai][0][m][0] * r, g1 = acc[ai][0][m][1] * r, u0 = acc[ai][1][m][0] * r, u1 = acc[ai][1][m][1] * r;
;                 u32x4 w;
;                 w.x = pk2(silu_f(g0[0]) * u0[0], silu_f(g0[1]) * u0[1]); w.y = pk2(silu_f(g0[2]) * u0[2], silu_f(g0[3]) * u0[3]);
;                 w.z = pk2(silu_f(g1[0]) * u1[0], silu_f(g1[1]) * u1[1]); w.w = pk2(silu_f(g1[2]) * u1[2], silu_f(g1[3]) * u1[3]);
;                 *(u32x4*)(H + (size_t)row * DFF + col0) = w;
;             }
	v_pk_mul_f32 v[88:89], v[88:89], v[206:207]
	v_pk_mul_f32 v[90:91], v[90:91], v[208:209]
	v_pk_mul_f32 v[84:85], v[84:85], v[210:211]
	v_pk_mul_f32 v[86:87], v[86:87], v[212:213]
	v_cvt_pk_bf16_f32 v88, v88, v89
	v_cvt_pk_bf16_f32 v89, v90, v91
	v_cvt_pk_bf16_f32 v90, v84, v85
	v_cvt_pk_bf16_f32 v91, v86, v87
	global_store_dwordx4 v215, v[88:91], s[94:95]
	v_mul_f32_e32 v200, 0xbfb8aa3b, v143
	v_mul_f32_e32 v202, v143, v143
	v_add_u32_e32 v215, 0x42000, v214
	v_pk_mul_f32 v[206:207], v[80:81], v[200:201] op_sel_hi:[1,0]
	v_pk_mul_f32 v[208:209], v[82:83], v[200:201] op_sel_hi:[1,0]
	v_pk_mul_f32 v[210:211], v[76:77], v[200:201] op_sel_hi:[1,0]
	v_pk_mul_f32 v[212:213], v[78:79], v[200:201] op_sel_hi:[1,0]
	v_exp_f32_e32 v206, v206
	v_exp_f32_e32 v207, v207
	v_exp_f32_e32 v208, v208
	v_exp_f32_e32 v209, v209
	v_exp_f32_e32 v210, v210
	v_exp_f32_e32 v211, v211
	v_exp_f32_e32 v212, v212
	v_exp_f32_e32 v213, v213
	v_pk_mul_f32 v[72:73], v[80:81], v[72:73]
	v_pk_mul_f32 v[74:75], v[82:83], v[74:75]
	v_pk_mul_f32 v[68:69], v[76:77], v[68:69]
	v_pk_mul_f32 v[70:71], v[78:79], v[70:71]
	v_pk_add_f32 v[206:207], v[206:207], v[204:205] op_sel_hi:[1,0]
	v_pk_add_f32 v[208:209], v[208:209], v[204:205] op_sel_hi:[1,0]
	v_pk_add_f32 v[210:211], v[210:211], v[204:205] op_sel_hi:[1,0]
	v_pk_add_f32 v[212:213], v[212:213], v[204:205] op_sel_hi:[1,0]
	v_rcp_f32_e32 v206, v206
	v_rcp_f32_e32 v207, v207
	v_rcp_f32_e32 v208, v208
	v_rcp_f32_e32 v209, v209
	v_rcp_f32_e32 v210, v210
	v_rcp_f32_e32 v211, v211
	v_rcp_f32_e32 v212, v212
	v_rcp_f32_e32 v213, v213
	v_pk_mul_f32 v[72:73], v[72:73], v[202:203] op_sel_hi:[1,0]
	v_pk_mul_f32 v[74:75], v[74:75], v[202:203] op_sel_hi:[1,0]
	v_pk_mul_f32 v[68:69], v[68:69], v[202:203] op_sel_hi:[1,0]
	v_pk_mul_f32 v[70:71], v[70:71], v[202:203] op_sel_hi:[1,0]
	v_pk_mul_f32 v[72:73], v[72:73], v[206:207]
	v_pk_mul_f32 v[74:75], v[74:75], v[208:209]
	v_pk_mul_f32 v[68:69], v[68:69], v[210:211]
	v_pk_mul_f32 v[70:71], v[70:71], v[212:213]
	v_cvt_pk_bf16_f32 v72, v72, v73
	v_cvt_pk_bf16_f32 v73, v74, v75
	v_cvt_pk_bf16_f32 v74, v68, v69
	v_cvt_pk_bf16_f32 v75, v70, v71
	global_store_dwordx4 v215, v[72:75], s[94:95]
	v_mul_f32_e32 v200, 0xbfb8aa3b, v156
	v_mul_f32_e32 v202, v156, v156
	v_add_u32_e32 v215, 0xb0000, v214
	v_pk_mul_f32 v[206:207], v[64:65], v[200:201] op_sel_hi:[1,0]
	v_pk_mul_f32 v[208:209], v[66:67], v[200:201] op_sel_hi:[1,0]
	v_pk_mul_f32 v[210:211], v[60:61], v[200:201] op_sel_hi:[1,0]
	v_pk_mul_f32 v[212:213], v[62:63], v[200:201] op_sel_hi:[1,0]
	v_exp_f32_e32 v206, v206
	v_exp_f32_e32 v207, v207
	v_exp_f32_e32 v208, v208
	v_exp_f32_e32 v209, v209
	v_exp_f32_e32 v210, v210
	v_exp_f32_e32 v211, v211
	v_exp_f32_e32 v212, v212
	v_exp_f32_e32 v213, v213
	v_pk_mul_f32 v[56:57], v[64:65], v[56:57]
	v_pk_mul_f32 v[58:59], v[66:67], v[58:59]
	v_pk_mul_f32 v[52:53], v[60:61], v[52:53]
	v_pk_mul_f32 v[54:55], v[62:63], v[54:55]
	v_pk_add_f32 v[206:207], v[206:207], v[204:205] op_sel_hi:[1,0]
	v_pk_add_f32 v[208:209], v[208:209], v[204:205] op_sel_hi:[1,0]
	v_pk_add_f32 v[210:211], v[210:211], v[204:205] op_sel_hi:[1,0]
	v_pk_add_f32 v[212:213], v[212:213], v[204:205] op_sel_hi:[1,0]
	v_rcp_f32_e32 v206, v206
	v_rcp_f32_e32 v207, v207
	v_rcp_f32_e32 v208, v208
	v_rcp_f32_e32 v209, v209
	v_rcp_f32_e32 v210, v210
	v_rcp_f32_e32 v211, v211
	v_rcp_f32_e32 v212, v212
	v_rcp_f32_e32 v213, v213
	v_pk_mul_f32 v[56:57], v[56:57], v[202:203] op_sel_hi:[1,0]
	v_pk_mul_f32 v[58:59], v[58:59], v[202:203] op_sel_hi:[1,0]
	v_pk_mul_f32 v[52:53], v[52:53], v[202:203] op_sel_hi:[1,0]
	v_pk_mul_f32 v[54:55], v[54:55], v[202:203] op_sel_hi:[1,0]
	v_pk_mul_f32 v[56:57], v[56:57], v[206:207]
	v_pk_mul_f32 v[58:59], v[58:59], v[208:209]
	v_pk_mul_f32 v[52:53], v[52:53], v[210:211]
	v_pk_mul_f32 v[54:55], v[54:55], v[212:213]
	v_cvt_pk_bf16_f32 v56, v56, v57
	v_cvt_pk_bf16_f32 v57, v58, v59
	v_cvt_pk_bf16_f32 v58, v52, v53
	v_cvt_pk_bf16_f32 v59, v54, v55
	global_store_dwordx4 v215, v[56:59], s[94:95]
	v_mul_f32_e32 v200, 0xbfb8aa3b, v157
	v_mul_f32_e32 v202, v157, v157
	v_add_u32_e32 v215, 0xc6000, v214
	v_pk_mul_f32 v[206:207], v[48:49], v[200:201] op_sel_hi:[1,0]
	v_pk_mul_f32 v[208:209], v[50:51], v[200:201] op_sel_hi:[1,0]
	v_pk_mul_f32 v[210:211], v[44:45], v[200:201] op_sel_hi:[1,0]
	v_pk_mul_f32 v[212:213], v[46:47], v[200:201] op_sel_hi:[1,0]
	v_exp_f32_e32 v206, v206
	v_exp_f32_e32 v207, v207
	v_exp_f32_e32 v208, v208
	v_exp_f32_e32 v209, v209
	v_exp_f32_e32 v210, v210
	v_exp_f32_e32 v211, v211
	v_exp_f32_e32 v212, v212
	v_exp_f32_e32 v213, v213
	v_pk_mul_f32 v[40:41], v[48:49], v[40:41]
	v_pk_mul_f32 v[42:43], v[50:51], v[42:43]
	v_pk_mul_f32 v[36:37], v[44:45], v[36:37]
	v_pk_mul_f32 v[38:39], v[46:47], v[38:39]
	v_pk_add_f32 v[206:207], v[206:207], v[204:205] op_sel_hi:[1,0]
	v_pk_add_f32 v[208:209], v[208:209], v[204:205] op_sel_hi:[1,0]
; __device__ __forceinline__ unsigned pk2(float lo, float hi) { f32x2 v = {lo, hi}; bf16x2_t b = __builtin_convertvector(v, bf16x2_t); return __builtin_bit_cast(unsigned, b); }
; __device__ __forceinline__ float silu_f(float g) { return g * __builtin_amdgcn_rcpf(1.f + __builtin_amdgcn_exp2f(g * -1.4426950408889634f)); }
; __device__ __forceinline__ void rstd_unit_start(RstdState& st, const float* ssq, int pm, int tid) {
;     if (pm != st.last_pm && tid < 256) st.pre = *(const f32x4*)(ssq + (size_t)(pm * BM + tid) * 4);
; }
;     __device__ __forceinline__ void operator()(const f32x4 (&acc)[2][2][4][2], const Unit& u, int wr, int wc, int fr, int fq, LAS unsigned char* lds, int tid, State& st) const {
;     ...
;             for (int m = 0; m < 4; ++m) {
;                 const int row = row0 + ai * HALF + m * 16; const float r = rs[m];
;                 const f32x4 g0 = acc[ai][0][m][0] * r, g1 = acc[ai][0][m][1] * r, u0 = acc[ai][1][m][0] * r, u1 = acc[ai][1][m][1] * r;
;                 u32x4 w;
;                 w.x = pk2(silu_f(g0[0]) * u0[0], silu_f(g0[1]) * u0[1]); w.y = pk2(silu_f(g0[2]) * u0[2], silu_f(g0[3]) * u0[3]);
;                 w.z = pk2(silu_f(g1[0]) * u1[0], silu_f(g1[1]) * u1[1]); w.w = pk2(silu_f(g1[2]) * u1[2], silu_f(g1[3]) * u1[3]);
;                 *(u32x4*)(H + (size_t)row * DFF + col0) = w;
;             }
	v_pk_add_f32 v[210:211], v[210:211], v[204:205] op_sel_hi:[1,0]
	v_pk_add_f32 v[212:213], v[212:213], v[204:205] op_sel_hi:[1,0]
	v_rcp_f32_e32 v206, v206
	v_rcp_f32_e32 v207, v207
	v_rcp_f32_e32 v208, v208
	v_rcp_f32_e32 v209, v209
	v_rcp_f32_e32 v210, v210
	v_rcp_f32_e32 v211, v211
	v_rcp_f32_e32 v212, v212
	v_rcp_f32_e32 v213, v213
	v_pk_mul_f32 v[40:41], v[40:41], v[202:203] op_sel_hi:[1,0]
	v_pk_mul_f32 v[42:43], v[42:43], v[202:203] op_sel_hi:[1,0]
	v_pk_mul_f32 v[36:37], v[36:37], v[202:203] op_sel_hi:[1,0]
	v_pk_mul_f32 v[38:39], v[38:39], v[202:203] op_sel_hi:[1,0]
	v_pk_mul_f32 v[40:41], v[40:41], v[206:207]
	v_pk_mul_f32 v[42:43], v[42:43], v[208:209]
	v_pk_mul_f32 v[36:37], v[36:37], v[210:211]
	v_pk_mul_f32 v[38:39], v[38:39], v[212:213]
	v_cvt_pk_bf16_f32 v40, v40, v41
	v_cvt_pk_bf16_f32 v41, v42, v43
	v_cvt_pk_bf16_f32 v42, v36, v37
	v_cvt_pk_bf16_f32 v43, v38, v39
	global_store_dwordx4 v215, v[40:43], s[94:95]
	v_mul_f32_e32 v200, 0xbfb8aa3b, v144
	v_mul_f32_e32 v202, v144, v144
	v_add_u32_e32 v215, 0xdc000, v214
	v_pk_mul_f32 v[206:207], v[32:33], v[200:201] op_sel_hi:[1,0]
	v_pk_mul_f32 v[208:209], v[34:35], v[200:201] op_sel_hi:[1,0]
	v_pk_mul_f32 v[210:211], v[28:29], v[200:201] op_sel_hi:[1,0]
	v_pk_mul_f32 v[212:213], v[30:31], v[200:201] op_sel_hi:[1,0]
	v_exp_f32_e32 v206, v206
	v_exp_f32_e32 v207, v207
	v_exp_f32_e32 v208, v208
	v_exp_f32_e32 v209, v209
	v_exp_f32_e32 v210, v210
	v_exp_f32_e32 v211, v211
	v_exp_f32_e32 v212, v212
	v_exp_f32_e32 v213, v213
	v_pk_mul_f32 v[24:25], v[32:33], v[24:25]
	v_pk_mul_f32 v[26:27], v[34:35], v[26:27]
	v_pk_mul_f32 v[20:21], v[28:29], v[20:21]
	v_pk_mul_f32 v[22:23], v[30:31], v[22:23]
	v_pk_add_f32 v[206:207], v[206:207], v[204:205] op_sel_hi:[1,0]
	v_pk_add_f32 v[208:209], v[208:209], v[204:205] op_sel_hi:[1,0]
	v_pk_add_f32 v[210:211], v[210:211], v[204:205] op_sel_hi:[1,0]
	v_pk_add_f32 v[212:213], v[212:213], v[204:205] op_sel_hi:[1,0]
	v_rcp_f32_e32 v206, v206
	v_rcp_f32_e32 v207, v207
	v_rcp_f32_e32 v208, v208
	v_rcp_f32_e32 v209, v209
	v_rcp_f32_e32 v210, v210
	v_rcp_f32_e32 v211, v211
	v_rcp_f32_e32 v212, v212
	v_rcp_f32_e32 v213, v213
	v_pk_mul_f32 v[24:25], v[24:25], v[202:203] op_sel_hi:[1,0]
	v_pk_mul_f32 v[26:27], v[26:27], v[202:203] op_sel_hi:[1,0]
	v_pk_mul_f32 v[20:21], v[20:21], v[202:203] op_sel_hi:[1,0]
	v_pk_mul_f32 v[22:23], v[22:23], v[202:203] op_sel_hi:[1,0]
	v_pk_mul_f32 v[24:25], v[24:25], v[206:207]
	v_pk_mul_f32 v[26:27], v[26:27], v[208:209]
	v_pk_mul_f32 v[20:21], v[20:21], v[210:211]
	v_pk_mul_f32 v[22:23], v[22:23], v[212:213]
	v_cvt_pk_bf16_f32 v24, v24, v25
	v_cvt_pk_bf16_f32 v25, v26, v27
	v_cvt_pk_bf16_f32 v26, v20, v21
	v_cvt_pk_bf16_f32 v27, v22, v23
	global_store_dwordx4 v215, v[24:27], s[94:95]
	v_mul_f32_e32 v200, 0xbfb8aa3b, v145
	v_mul_f32_e32 v202, v145, v145
	v_add_u32_e32 v215, 0xf2000, v214
	v_pk_mul_f32 v[206:207], v[16:17], v[200:201] op_sel_hi:[1,0]
	v_pk_mul_f32 v[208:209], v[18:19], v[200:201] op_sel_hi:[1,0]
	v_pk_mul_f32 v[210:211], v[12:13], v[200:201] op_sel_hi:[1,0]
	v_pk_mul_f32 v[212:213], v[14:15], v[200:201] op_sel_hi:[1,0]
	v_exp_f32_e32 v206, v206
	v_exp_f32_e32 v207, v207
	v_exp_f32_e32 v208, v208
	v_exp_f32_e32 v209, v209
	v_exp_f32_e32 v210, v210
	v_exp_f32_e32 v211, v211
	v_exp_f32_e32 v212, v212
	v_exp_f32_e32 v213, v213
	v_pk_mul_f32 v[8:9], v[16:17], v[8:9]
	v_pk_mul_f32 v[10:11], v[18:19], v[10:11]
	v_pk_mul_f32 v[4:5], v[12:13], v[4:5]
	v_pk_mul_f32 v[6:7], v[14:15], v[6:7]
	v_pk_add_f32 v[206:207], v[206:207], v[204:205] op_sel_hi:[1,0]
	v_pk_add_f32 v[208:209], v[208:209], v[204:205] op_sel_hi:[1,0]
	v_pk_add_f32 v[210:211], v[210:211], v[204:205] op_sel_hi:[1,0]
	v_pk_add_f32 v[212:213], v[212:213], v[204:205] op_sel_hi:[1,0]
	v_rcp_f32_e32 v206, v206
	v_rcp_f32_e32 v207, v207
	v_rcp_f32_e32 v208, v208
	v_rcp_f32_e32 v209, v209
	v_rcp_f32_e32 v210, v210
	v_rcp_f32_e32 v211, v211
	v_rcp_f32_e32 v212, v212
	v_rcp_f32_e32 v213, v213
	v_pk_mul_f32 v[8:9], v[8:9], v[202:203] op_sel_hi:[1,0]
	v_pk_mul_f32 v[10:11], v[10:11], v[202:203] op_sel_hi:[1,0]
	v_pk_mul_f32 v[4:5], v[4:5], v[202:203] op_sel_hi:[1,0]
	v_pk_mul_f32 v[6:7], v[6:7], v[202:203] op_sel_hi:[1,0]
	v_pk_mul_f32 v[8:9], v[8:9], v[206:207]
	v_pk_mul_f32 v[10:11], v[10:11], v[208:209]
	v_pk_mul_f32 v[4:5], v[4:5], v[210:211]
	v_pk_mul_f32 v[6:7], v[6:7], v[212:213]
	v_cvt_pk_bf16_f32 v8, v8, v9
	v_cvt_pk_bf16_f32 v9, v10, v11
	v_cvt_pk_bf16_f32 v10, v4, v5
	v_cvt_pk_bf16_f32 v11, v6, v7
	global_store_dwordx4 v215, v[8:11], s[94:95]
	s_mov_b64 s[6:7], -1
	s_cbranch_vccnz .LBB0_713
	s_cmp_lg_u32 s22, s9
	s_cselect_b64 s[6:7], -1, 0
	s_and_b64 s[14:15], s[38:39], s[6:7]
	s_and_saveexec_b64 s[6:7], s[14:15]
	s_cbranch_execz .LBB0_728
	s_waitcnt vmcnt(0)
	v_lshl_add_u32 v0, s22, 8, v146
	v_ashrrev_i32_e32 v1, 31, v0
	v_lshl_add_u64 v[0:1], v[0:1], 4, s[88:89]
	global_load_dwordx4 v[0:3], v[0:1], off
